# DA loop: K/V tile ds_writes (and the V tile loads) spread over the MFMA gaps of slots 1 and 2 instead of bunched at the barriers; staging of the tile after the last one no longer branched around
# speedup vs baseline: 1.0150x; 1.0114x over previous
; __device__ void da_unit(char* lds, const Params& p, int layer, int unit) {
;     ...
;         const int kt = tile_of(it);
;         const char* cK = lds + (it & 1) * DA_STAGE;
;         const char* cV = cK + DA_KBYTES;
;         char* nK = lds + ((it + 1) & 1) * DA_STAGE;
;         const int tn = tile_of(it + 1 < NT ? it + 1 : it);
;         if (it + 1 < NT) {
; #pragma unroll
;             for (int j = 0; j < 4; ++j) rk[j] = *(const u32x4*)(Kg + (size_t)tn * 16384 + j * 4096);
;         }
;     ...
;         if (it + 1 < NT) {
; #pragma unroll
;             for (int j = 0; j < 4; ++j) *(u32x4*)(nK + (kr_ + 32 * j) * DA_KP + kc_ * 16) = rk[j];
; #pragma unroll
;             for (int j = 0; j < 4; ++j) rk[j] = *(const u32x4*)(Vg + (size_t)tn * 16384 + j * 4096);
;         }
.Lda_noflip:
	s_add_i32 s0, s14, s4
	s_sub_i32 s1, 15, s4
	s_cmp_lt_u32 s4, s9
	s_cselect_b32 s10, s0, s1
	s_lshl_b32 s11, s10, 7
	s_add_i32 s16, s4, 1
	s_add_i32 s0, s14, s16
	s_sub_i32 s1, 15, s16
	s_cmp_lt_u32 s16, s9
	s_cselect_b32 s0, s0, s1
	s_max_i32 s0, s0, 0
	s_add_i32 s16, s4, 2
	s_add_i32 s3, s14, s16
	s_sub_i32 s1, 15, s16
	s_cmp_lt_u32 s16, s9
	s_cselect_b32 s3, s3, s1
	s_bitcmp1_b32 s4, 0
	s_cselect_b32 s17, 0x11800, 0
	s_sub_i32 s5, 0x11800, s17
	s_add_i32 s1, s17, s8
	s_add_i32 s2, s17, 0x8800
	v_add3_u32 v234, s1, v186, v152
	v_add3_u32 v235, s2, v152, v154
	s_add_i32 s1, s5, s8
	s_add_i32 s2, s5, 0x8800
	v_add3_u32 v236, s1, v186, v152
	v_add3_u32 v178, s2, v152, v154
	v_cvt_f32_u32_e32 v242, s11
	v_add_f32_e32 v242, v185, v242
	v_fma_f32 v239, v242, v250, v169
	v_fma_f32 v253, v242, -v250, v64
	v_sub_f32_e32 v241, v169, v253
	v_mfma_f32_32x32x16_bf16 v[98:113], v[210:213], v[114:117], v[66:81]
	ds_read_b128 v[210:213], v234 offset:17408
	v_sub_f32_e32 v82, v82, v239
	v_sub_f32_e32 v83, v83, v239
	v_sub_f32_e32 v84, v84, v239
	v_sub_f32_e32 v85, v85, v239
	v_exp_f32_e32 v82, v82
	v_mfma_f32_32x32x16_bf16 v[48:63], v[226:229], v[202:205], v[48:63]
	ds_read_b128 v[226:229], v178 offset:18528
	v_exp_f32_e32 v83, v83
	v_exp_f32_e32 v84, v84
	v_exp_f32_e32 v85, v85
	v_mfma_f32_32x32x16_bf16 v[32:47], v[230:233], v[202:205], v[32:47]
	ds_read_b128 v[230:233], v178 offset:23136
	v_add_f32_e32 v191, v191, v82
	v_add_f32_e32 v192, v192, v83
	v_cvt_pk_bf16_f32 v194, v82, v83
	v_add_f32_e32 v191, v191, v84
	v_add_f32_e32 v192, v192, v85
	v_cvt_pk_bf16_f32 v195, v84, v85
	v_mfma_f32_32x32x16_bf16 v[98:113], v[214:217], v[118:121], v[98:113]
	ds_read_b128 v[214:217], v234 offset:17440
	v_sub_f32_e32 v86, v86, v239
	v_sub_f32_e32 v87, v87, v239
	v_sub_f32_e32 v88, v88, v239
	v_sub_f32_e32 v89, v89, v239
	v_exp_f32_e32 v86, v86
	v_mfma_f32_32x32x16_bf16 v[16:31], v[174:177], v[202:205], v[16:31]
	ds_read_b128 v[174:177], v178 offset:27744
	v_exp_f32_e32 v87, v87
	v_exp_f32_e32 v88, v88
	v_exp_f32_e32 v89, v89
	v_mfma_f32_32x32x16_bf16 v[0:15], v[246:249], v[202:205], v[0:15]
	ds_read_b128 v[246:249], v178 offset:32352
	v_add_f32_e32 v191, v191, v86
	v_add_f32_e32 v192, v192, v87
	v_cvt_pk_bf16_f32 v196, v86, v87
	v_add_f32_e32 v191, v191, v88
	v_add_f32_e32 v192, v192, v89
	v_cvt_pk_bf16_f32 v197, v88, v89
	v_mfma_f32_32x32x16_bf16 v[98:113], v[218:221], v[122:125], v[98:113]
	ds_read_b128 v[218:221], v234 offset:17472
	v_sub_f32_e32 v90, v90, v239
	v_sub_f32_e32 v91, v91, v239
	v_sub_f32_e32 v92, v92, v239
	v_sub_f32_e32 v93, v93, v239
	v_exp_f32_e32 v90, v90
	s_waitcnt lgkmcnt(5)
	v_mfma_f32_32x32x16_bf16 v[48:63], v[226:229], v[206:209], v[48:63]
	ds_read_b128 v[226:229], v235 offset:0
	v_exp_f32_e32 v91, v91
	v_exp_f32_e32 v92, v92
	v_exp_f32_e32 v93, v93
	s_waitcnt lgkmcnt(5)
	v_mfma_f32_32x32x16_bf16 v[32:47], v[230:233], v[206:209], v[32:47]
	ds_read_b128 v[230:233], v235 offset:4608
	v_add_f32_e32 v191, v191, v90
	v_add_f32_e32 v192, v192, v91
	v_cvt_pk_bf16_f32 v198, v90, v91
	v_add_f32_e32 v191, v191, v92
	v_add_f32_e32 v192, v192, v93
	v_cvt_pk_bf16_f32 v199, v92, v93
	v_mfma_f32_32x32x16_bf16 v[98:113], v[222:225], v[126:129], v[98:113]
	ds_read_b128 v[222:225], v234 offset:17504
	v_sub_f32_e32 v94, v94, v239
	v_sub_f32_e32 v95, v95, v239
	v_sub_f32_e32 v96, v96, v239
	v_sub_f32_e32 v97, v97, v239
	v_exp_f32_e32 v94, v94
	s_waitcnt lgkmcnt(5)
	v_mfma_f32_32x32x16_bf16 v[16:31], v[174:177], v[206:209], v[16:31]
	ds_read_b128 v[174:177], v235 offset:9216
	v_exp_f32_e32 v95, v95
	v_exp_f32_e32 v96, v96
	v_exp_f32_e32 v97, v97
	s_waitcnt lgkmcnt(5)
	v_mfma_f32_32x32x16_bf16 v[0:15], v[246:249], v[206:209], v[0:15]
	ds_read_b128 v[246:249], v235 offset:13824
	v_add_f32_e32 v191, v191, v94
	v_add_f32_e32 v192, v192, v95
	v_cvt_pk_bf16_f32 v200, v94, v95
	v_add_f32_e32 v191, v191, v96
	v_add_f32_e32 v192, v192, v97
	v_cvt_pk_bf16_f32 v201, v96, v97
	s_waitcnt lgkmcnt(0)
	s_barrier
	v_mfma_f32_32x32x16_bf16 v[82:97], v[210:213], v[114:117], v[66:81]
	ds_read_b128 v[210:213], v234 offset:26112
	v_add3_u32 v158, s5, v180, v182
	v_sub_f32_e32 v98, v98, v241
	v_sub_f32_e32 v99, v99, v241
	v_sub_f32_e32 v100, v100, v241
	v_sub_f32_e32 v101, v101, v241
	v_exp_f32_e32 v98, v98
	v_mfma_f32_32x32x16_bf16 v[48:63], v[226:229], v[194:197], v[48:63]
	ds_read_b128 v[226:229], v235 offset:32
	s_waitcnt vmcnt(3)
	ds_write_b128 v158, v[130:133] offset:0
	s_lshl_b32 s18, s0, 15
	s_mov_b32 s19, 0
	v_lshl_add_u64 v[156:157], v[150:151], 0, s[18:19]
	global_load_dwordx4 v[130:133], v[156:157], off
	v_exp_f32_e32 v99, v99
	v_exp_f32_e32 v100, v100
	v_exp_f32_e32 v101, v101
	v_mfma_f32_32x32x16_bf16 v[32:47], v[230:233], v[194:197], v[32:47]
	ds_read_b128 v[230:233], v235 offset:4640
	v_add_f32_e32 v191, v191, v98
	v_add_f32_e32 v192, v192, v99
	v_cvt_pk_bf16_f32 v202, v98, v99
	v_add_f32_e32 v191, v191, v100
	v_add_f32_e32 v192, v192, v101
	v_cvt_pk_bf16_f32 v203, v100, v101
	v_mfma_f32_32x32x16_bf16 v[82:97], v[214:217], v[118:121], v[82:97]
	ds_read_b128 v[214:217], v234 offset:26144
	s_waitcnt vmcnt(3)
	ds_write_b128 v158, v[134:137] offset:8704
	s_add_u32 s18, s18, 0x2000
	v_lshl_add_u64 v[156:157], v[150:151], 0, s[18:19]
	global_load_dwordx4 v[134:137], v[156:157], off
	v_sub_f32_e32 v102, v102, v241
	v_sub_f32_e32 v103, v103, v241
	v_sub_f32_e32 v104, v104, v241
	v_sub_f32_e32 v105, v105, v241
	v_exp_f32_e32 v102, v102
	v_mfma_f32_32x32x16_bf16 v[16:31], v[174:177], v[194:197], v[16:31]
	ds_read_b128 v[174:177], v235 offset:9248
	v_exp_f32_e32 v103, v103
	v_exp_f32_e32 v104, v104
	v_exp_f32_e32 v105, v105
	v_mfma_f32_32x32x16_bf16 v[0:15], v[246:249], v[194:197], v[0:15]
	ds_read_b128 v[246:249], v235 offset:13856
	s_waitcnt vmcnt(3)
; __device__ void da_unit(char* lds, const Params& p, int layer, int unit) {
;     ...
;         DA_FAST_HALF(Bs, -slope2, 0)
;         if (it + 1 < NT) {
; #pragma unroll
;             for (int j = 0; j < 4; ++j) *(u32x4*)(nK + (kr_ + 32 * j) * DA_KP + kc_ * 16) = rk[j];
; #pragma unroll
;             for (int j = 0; j < 4; ++j) rk[j] = *(const u32x4*)(Vg + (size_t)tn * 16384 + j * 4096);
;         }
;         DA_FAST_HALF(Bs, -slope2, 1)
;     ...
;         if (it + 1 < NT) {
; #pragma unroll
;             for (int j = 0; j < 4; ++j) *(u32x4*)(nK + DA_KBYTES + (j >> 1) * DA_VSUB + (vr_ + 64 * (j & 1)) * DA_VP + vc_ * 16) = rk[j];
	ds_write_b128 v158, v[138:141] offset:17408
	s_add_u32 s18, s18, 0x2000
	v_lshl_add_u64 v[156:157], v[150:151], 0, s[18:19]
	global_load_dwordx4 v[138:141], v[156:157], off
	v_add_f32_e32 v191, v191, v102
	v_add_f32_e32 v192, v192, v103
	v_cvt_pk_bf16_f32 v204, v102, v103
	v_add_f32_e32 v191, v191, v104
	v_add_f32_e32 v192, v192, v105
	v_cvt_pk_bf16_f32 v205, v104, v105
	v_mfma_f32_32x32x16_bf16 v[82:97], v[218:221], v[122:125], v[82:97]
	ds_read_b128 v[218:221], v234 offset:26176
	v_sub_f32_e32 v106, v106, v241
	v_sub_f32_e32 v107, v107, v241
	v_sub_f32_e32 v108, v108, v241
	v_sub_f32_e32 v109, v109, v241
	v_exp_f32_e32 v106, v106
	s_waitcnt lgkmcnt(8)
	v_mfma_f32_32x32x16_bf16 v[48:63], v[226:229], v[198:201], v[48:63]
	ds_read_b128 v[226:229], v235 offset:64
	s_waitcnt vmcnt(3)
	ds_write_b128 v158, v[142:145] offset:26112
	s_add_u32 s18, s18, 0x2000
	v_lshl_add_u64 v[156:157], v[150:151], 0, s[18:19]
	global_load_dwordx4 v[142:145], v[156:157], off
	v_exp_f32_e32 v107, v107
	v_exp_f32_e32 v108, v108
	v_exp_f32_e32 v109, v109
	s_waitcnt lgkmcnt(8)
	v_mfma_f32_32x32x16_bf16 v[32:47], v[230:233], v[198:201], v[32:47]
	ds_read_b128 v[230:233], v235 offset:4672
	v_add_f32_e32 v191, v191, v106
	v_add_f32_e32 v192, v192, v107
	v_cvt_pk_bf16_f32 v206, v106, v107
	v_add_f32_e32 v191, v191, v108
	v_add_f32_e32 v192, v192, v109
	v_cvt_pk_bf16_f32 v207, v108, v109
	v_mfma_f32_32x32x16_bf16 v[82:97], v[222:225], v[126:129], v[82:97]
	ds_read_b128 v[222:225], v234 offset:26208
	v_sub_f32_e32 v110, v110, v241
	v_sub_f32_e32 v111, v111, v241
	v_sub_f32_e32 v112, v112, v241
	v_sub_f32_e32 v113, v113, v241
	v_exp_f32_e32 v110, v110
	s_waitcnt lgkmcnt(7)
	v_mfma_f32_32x32x16_bf16 v[16:31], v[174:177], v[198:201], v[16:31]
	ds_read_b128 v[174:177], v235 offset:9280
	v_exp_f32_e32 v111, v111
	v_exp_f32_e32 v112, v112
	v_exp_f32_e32 v113, v113
	s_waitcnt lgkmcnt(7)
	v_mfma_f32_32x32x16_bf16 v[0:15], v[246:249], v[198:201], v[0:15]
	ds_read_b128 v[246:249], v235 offset:13888
	v_add_f32_e32 v191, v191, v110
	v_add_f32_e32 v192, v192, v111
	v_cvt_pk_bf16_f32 v208, v110, v111
	v_add_f32_e32 v191, v191, v112
	v_add_f32_e32 v192, v192, v113
	v_cvt_pk_bf16_f32 v209, v112, v113
	s_or_b32 s2, s11, 64
	v_cvt_f32_u32_e32 v242, s2
	v_add_f32_e32 v242, v185, v242
	v_fma_f32 v239, v242, v250, v169
	v_fma_f32 v253, v242, -v250, v64
	v_sub_f32_e32 v241, v169, v253
	v_mfma_f32_32x32x16_bf16 v[98:113], v[210:213], v[114:117], v[66:81]
	v_sub_f32_e32 v82, v82, v239
	v_sub_f32_e32 v83, v83, v239
	v_sub_f32_e32 v84, v84, v239
	v_sub_f32_e32 v85, v85, v239
	v_exp_f32_e32 v82, v82
	s_waitcnt lgkmcnt(5)
	v_mfma_f32_32x32x16_bf16 v[48:63], v[226:229], v[202:205], v[48:63]
	ds_read_b128 v[226:229], v235 offset:96
	v_exp_f32_e32 v83, v83
	v_exp_f32_e32 v84, v84
	v_exp_f32_e32 v85, v85
	s_waitcnt lgkmcnt(4)
	v_mfma_f32_32x32x16_bf16 v[32:47], v[230:233], v[202:205], v[32:47]
	ds_read_b128 v[230:233], v235 offset:4704
	v_add_f32_e32 v191, v191, v82
	v_add_f32_e32 v192, v192, v83
	v_cvt_pk_bf16_f32 v194, v82, v83
	v_add_f32_e32 v191, v191, v84
	v_add_f32_e32 v192, v192, v85
	v_cvt_pk_bf16_f32 v195, v84, v85
	v_mfma_f32_32x32x16_bf16 v[98:113], v[214:217], v[118:121], v[98:113]
	v_sub_f32_e32 v86, v86, v239
	v_sub_f32_e32 v87, v87, v239
	v_sub_f32_e32 v88, v88, v239
	v_sub_f32_e32 v89, v89, v239
	v_exp_f32_e32 v86, v86
	s_waitcnt lgkmcnt(3)
	v_mfma_f32_32x32x16_bf16 v[16:31], v[174:177], v[202:205], v[16:31]
	ds_read_b128 v[174:177], v235 offset:9312
	v_exp_f32_e32 v87, v87
	v_exp_f32_e32 v88, v88
	v_exp_f32_e32 v89, v89
	s_waitcnt lgkmcnt(3)
	v_mfma_f32_32x32x16_bf16 v[0:15], v[246:249], v[202:205], v[0:15]
	ds_read_b128 v[246:249], v235 offset:13920
	v_add3_u32 v158, s5, v183, v181
	v_add_f32_e32 v191, v191, v86
	v_add_f32_e32 v192, v192, v87
	v_cvt_pk_bf16_f32 v196, v86, v87
	v_add_f32_e32 v191, v191, v88
	v_add_f32_e32 v192, v192, v89
	v_cvt_pk_bf16_f32 v197, v88, v89
	v_mfma_f32_32x32x16_bf16 v[98:113], v[218:221], v[122:125], v[98:113]
	s_waitcnt vmcnt(3)
	ds_write_b128 v158, v[130:133] offset:34816
	v_sub_f32_e32 v90, v90, v239
	v_sub_f32_e32 v91, v91, v239
	v_sub_f32_e32 v92, v92, v239
	v_sub_f32_e32 v93, v93, v239
	v_exp_f32_e32 v90, v90
	s_waitcnt lgkmcnt(4)
	v_mfma_f32_32x32x16_bf16 v[48:63], v[226:229], v[206:209], v[48:63]
	ds_read_b128 v[226:229], v235 offset:18432
	s_waitcnt vmcnt(2)
	ds_write_b128 v158, v[134:137] offset:44032
	v_exp_f32_e32 v91, v91
	v_exp_f32_e32 v92, v92
	v_exp_f32_e32 v93, v93
	s_waitcnt lgkmcnt(5)
	v_mfma_f32_32x32x16_bf16 v[32:47], v[230:233], v[206:209], v[32:47]
	ds_read_b128 v[230:233], v235 offset:23040
	s_waitcnt vmcnt(1)
	ds_write_b128 v158, v[138:141] offset:53248
	v_add_f32_e32 v191, v191, v90
	v_add_f32_e32 v192, v192, v91
	v_cvt_pk_bf16_f32 v198, v90, v91
	v_add_f32_e32 v191, v191, v92
	v_add_f32_e32 v192, v192, v93
	v_cvt_pk_bf16_f32 v199, v92, v93
	v_mfma_f32_32x32x16_bf16 v[98:113], v[222:225], v[126:129], v[98:113]
	s_waitcnt vmcnt(0)
	ds_write_b128 v158, v[142:145] offset:62464
	v_sub_f32_e32 v94, v94, v239
	v_sub_f32_e32 v95, v95, v239
	v_sub_f32_e32 v96, v96, v239
	v_sub_f32_e32 v97, v97, v239
	v_exp_f32_e32 v94, v94
	s_waitcnt lgkmcnt(7)
	v_mfma_f32_32x32x16_bf16 v[16:31], v[174:177], v[206:209], v[16:31]
	ds_read_b128 v[174:177], v235 offset:27648
	v_exp_f32_e32 v95, v95
	v_exp_f32_e32 v96, v96
	v_exp_f32_e32 v97, v97
	s_waitcnt lgkmcnt(7)
	v_mfma_f32_32x32x16_bf16 v[0:15], v[246:249], v[206:209], v[0:15]
	ds_read_b128 v[246:249], v235 offset:32256
	v_add_f32_e32 v191, v191, v94
	v_add_f32_e32 v192, v192, v95
	v_cvt_pk_bf16_f32 v200, v94, v95
	v_add_f32_e32 v191, v191, v96
	v_add_f32_e32 v192, v192, v97
	v_cvt_pk_bf16_f32 v201, v96, v97
	s_waitcnt lgkmcnt(0)
	s_barrier
	s_cmp_lt_u32 s4, 14
	s_cbranch_scc0 .Lda_nok
	s_lshl_b32 s18, s3, 15
	s_mov_b32 s19, 0
	v_lshl_add_u64 v[156:157], v[148:149], 0, s[18:19]
	global_load_dwordx4 v[130:133], v[156:157], off
	s_add_u32 s18, s18, 0x2000
	v_lshl_add_u64 v[156:157], v[148:149], 0, s[18:19]
	global_load_dwordx4 v[134:137], v[156:157], off
	s_add_u32 s18, s18, 0x2000
	v_lshl_add_u64 v[156:157], v[148:149], 0, s[18:19]
	global_load_dwordx4 v[138:141], v[156:157], off
	s_add_u32 s18, s18, 0x2000
	v_lshl_add_u64 v[156:157], v[148:149], 0, s[18:19]
	global_load_dwordx4 v[142:145], v[156:157], off
